# conv-FFN epilogue: the 8 per-tile weight/bias vector loads issued before the C-tile staging (into fragment registers) instead of after its barrier
# speedup vs baseline: 1.0045x; 1.0001x over previous
; template <int EPI>
; DI void phase_gemm(const Params& p, const GemmArgs& ga, char* lds) {
;     ...
;     } else {
;       __syncthreads();
;       constexpr int RS = 520;
;       {
;         char* wbase = lds + (wm * 128 + r) * RS + (wn * 64 + 4 * h) * 2;
; #pragma unroll
;         for (int mi = 0; mi < 4; ++mi)
; #pragma unroll
;           for (int ni = 0; ni < 2; ++ni)
; #pragma unroll
;             for (int j = 0; j < 4; ++j) {
;               u32x2 v = {pk_bf16(acc[mi][ni][4 * j], acc[mi][ni][4 * j + 1]), pk_bf16(acc[mi][ni][4 * j + 2], acc[mi][ni][4 * j + 3])};
;               *(u32x2*)(wbase + mi * 32 * RS + (ni * 32 + 8 * j) * 2) = v;
;             }
;       }
;       __syncthreads();
;       {
;         const int q4 = tid & 31, seg = tid >> 5;
;         const int ch = nt * 128 + 4 * q4;
;         const float* cw = p.ffn_conv_w + (size_t)ga.layer * 3 * 5632;
;         const float* cb = p.ffn_conv_b + (size_t)ga.layer * 5632;
;         float4 wg[3], wv[3];
; #pragma unroll
;         for (int t3 = 0; t3 < 3; ++t3) { wg[t3] = *(const float4*)(cw + t3 * 5632 + ch); wv[t3] = *(const float4*)(cw + t3 * 5632 + DFF + ch); }
;         const float4 bg = *(const float4*)(cb + ch);
;         const float4 bv = *(const float4*)(cb + DFF + ch);
;         const char* gbase = lds + q4 * 8;
;         const char* vbase = lds + 256 + q4 * 8;
;         const int R0 = 1 + seg * 16;
;         const int Rend = (R0 + 16 < 255) ? (R0 + 16) : 255;
;         auto ld4 = [&](const char* b_, int R) -> float4 {
;           const u32x2 u = *(const u32x2*)(b_ + R * RS);
;           float4 f = {__uint_as_float(u.x << 16), __uint_as_float(u.x & 0xffff0000u), __uint_as_float(u.y << 16), __uint_as_float(u.y & 0xffff0000u)};
;           return f;
;         };
;         float4 pg = ld4(gbase, R0 - 1), pvv = ld4(vbase, R0 - 1);
;         float4 cg_ = ld4(gbase, R0), cv_ = ld4(vbase, R0);
.Lg8_u0_join:
.LBB0_61:
	s_and_saveexec_b64 s[14:15], vcc
	v_lshl_or_b32 v158, s28, 7, v157
	v_ashrrev_i32_e32 v159, 31, v158
	v_lshlrev_b64 v[160:161], 2, v[158:159]
	v_readlane_b32 s10, v253, 19
	v_readlane_b32 s11, v253, 20
	s_nop 1
	v_lshl_add_u64 v[130:131], s[10:11], 0, v[160:161]
	v_readlane_b32 s10, v253, 21
	v_readlane_b32 s11, v253, 22
	s_nop 1
	v_lshl_add_u64 v[134:135], s[10:11], 0, v[160:161]
	v_readlane_b32 s10, v253, 23
	v_readlane_b32 s11, v253, 24
	s_nop 1
	v_lshl_add_u64 v[138:139], s[10:11], 0, v[160:161]
	v_readlane_b32 s10, v253, 25
	v_readlane_b32 s11, v253, 26
	s_nop 1
	v_lshl_add_u64 v[142:143], s[10:11], 0, v[160:161]
	v_readlane_b32 s10, v253, 27
	v_readlane_b32 s11, v253, 28
	s_nop 1
	v_lshl_add_u64 v[146:147], s[10:11], 0, v[160:161]
	v_readlane_b32 s10, v253, 29
	v_readlane_b32 s11, v253, 30
	s_nop 1
	v_lshl_add_u64 v[150:151], s[10:11], 0, v[160:161]
	v_readlane_b32 s10, v253, 31
	v_readlane_b32 s11, v253, 32
	s_nop 1
	v_lshl_add_u64 v[176:177], s[10:11], 0, v[160:161]
	v_readlane_b32 s10, v253, 33
	v_readlane_b32 s11, v253, 34
	s_nop 1
	v_lshl_add_u64 v[180:181], s[10:11], 0, v[160:161]
	global_load_dwordx4 v[130:133], v[130:131], off
	global_load_dwordx4 v[134:137], v[134:135], off
	global_load_dwordx4 v[138:141], v[138:139], off
	global_load_dwordx4 v[142:145], v[142:143], off
	global_load_dwordx4 v[146:149], v[146:147], off
	global_load_dwordx4 v[150:153], v[150:151], off
	global_load_dwordx4 v[176:179], v[176:177], off
	global_load_dwordx4 v[180:183], v[180:181], off
	s_or_b64 exec, exec, s[14:15]
	v_add_u32_e32 v0, 0x4000, v173
	s_barrier
	s_nop 8
	v_cvt_pk_bf16_f32 v82, v82, v83
	v_cvt_pk_bf16_f32 v83, v84, v85
	v_cvt_pk_bf16_f32 v84, v86, v87
	v_cvt_pk_bf16_f32 v85, v88, v89
	ds_write2_b64 v0, v[82:83], v[84:85] offset0:32 offset1:34
	v_cvt_pk_bf16_f32 v82, v90, v91
	v_cvt_pk_bf16_f32 v83, v92, v93
	v_cvt_pk_bf16_f32 v66, v66, v67
	v_cvt_pk_bf16_f32 v67, v68, v69
	v_cvt_pk_bf16_f32 v68, v70, v71
	v_cvt_pk_bf16_f32 v69, v72, v73
	v_cvt_pk_bf16_f32 v84, v94, v95
	v_cvt_pk_bf16_f32 v85, v96, v97
	ds_write2_b64 v0, v[66:67], v[68:69] offset0:40 offset1:42
	v_cvt_pk_bf16_f32 v66, v74, v75
	v_cvt_pk_bf16_f32 v67, v76, v77
	v_cvt_pk_bf16_f32 v68, v78, v79
	v_cvt_pk_bf16_f32 v69, v80, v81
	ds_write2_b64 v0, v[82:83], v[84:85] offset0:36 offset1:38
	ds_write2_b64 v0, v[66:67], v[68:69] offset0:44 offset1:46
	v_cvt_pk_bf16_f32 v50, v50, v51
	v_cvt_pk_bf16_f32 v51, v52, v53
	v_cvt_pk_bf16_f32 v52, v54, v55
	v_cvt_pk_bf16_f32 v53, v56, v57
	v_add_u32_e32 v0, 0x8000, v173
	v_cvt_pk_bf16_f32 v34, v34, v35
	v_cvt_pk_bf16_f32 v35, v36, v37
	v_cvt_pk_bf16_f32 v36, v38, v39
	v_cvt_pk_bf16_f32 v37, v40, v41
	ds_write2_b64 v0, v[50:51], v[52:53] offset0:64 offset1:66
	v_cvt_pk_bf16_f32 v50, v58, v59
	v_cvt_pk_bf16_f32 v51, v60, v61
	v_cvt_pk_bf16_f32 v52, v62, v63
	v_cvt_pk_bf16_f32 v53, v64, v65
	ds_write2_b64 v0, v[34:35], v[36:37] offset0:72 offset1:74
	v_cvt_pk_bf16_f32 v34, v42, v43
	v_cvt_pk_bf16_f32 v35, v44, v45
	v_cvt_pk_bf16_f32 v36, v46, v47
	v_cvt_pk_bf16_f32 v37, v48, v49
	v_cvt_pk_bf16_f32 v114, v114, v115
	v_cvt_pk_bf16_f32 v115, v116, v117
	v_cvt_pk_bf16_f32 v116, v118, v119
	v_cvt_pk_bf16_f32 v117, v120, v121
	v_cvt_pk_bf16_f32 v98, v98, v99
	v_cvt_pk_bf16_f32 v99, v100, v101
	v_cvt_pk_bf16_f32 v100, v102, v103
	v_cvt_pk_bf16_f32 v101, v104, v105
	ds_write2_b64 v0, v[50:51], v[52:53] offset0:68 offset1:70
	ds_write2_b64 v0, v[34:35], v[36:37] offset0:76 offset1:78
	v_cvt_pk_bf16_f32 v18, v18, v19
	v_cvt_pk_bf16_f32 v19, v20, v21
	v_cvt_pk_bf16_f32 v20, v22, v23
	v_cvt_pk_bf16_f32 v21, v24, v25
	v_add_u32_e32 v0, 0xc000, v173
	v_cvt_pk_bf16_f32 v2, v2, v3
	v_cvt_pk_bf16_f32 v3, v4, v5
	v_cvt_pk_bf16_f32 v4, v6, v7
	v_cvt_pk_bf16_f32 v5, v8, v9
	ds_write2_b64 v173, v[114:115], v[116:117] offset1:2
	v_cvt_pk_bf16_f32 v114, v122, v123
	v_cvt_pk_bf16_f32 v115, v124, v125
	v_cvt_pk_bf16_f32 v116, v126, v127
	v_cvt_pk_bf16_f32 v117, v128, v129
	ds_write2_b64 v173, v[98:99], v[100:101] offset0:8 offset1:10
	v_cvt_pk_bf16_f32 v98, v106, v107
	v_cvt_pk_bf16_f32 v99, v108, v109
	v_cvt_pk_bf16_f32 v100, v110, v111
	v_cvt_pk_bf16_f32 v101, v112, v113
	ds_write2_b64 v0, v[18:19], v[20:21] offset0:96 offset1:98
	v_cvt_pk_bf16_f32 v18, v26, v27
	v_cvt_pk_bf16_f32 v19, v28, v29
	v_cvt_pk_bf16_f32 v20, v30, v31
	v_cvt_pk_bf16_f32 v21, v32, v33
	ds_write2_b64 v0, v[2:3], v[4:5] offset0:104 offset1:106
	v_cvt_pk_bf16_f32 v2, v10, v11
	v_cvt_pk_bf16_f32 v3, v12, v13
	v_cvt_pk_bf16_f32 v4, v14, v15
	v_cvt_pk_bf16_f32 v5, v16, v17
	ds_write2_b64 v173, v[114:115], v[116:117] offset0:4 offset1:6
	ds_write2_b64 v173, v[98:99], v[100:101] offset0:12 offset1:14
	ds_write2_b64 v0, v[18:19], v[20:21] offset0:100 offset1:102
	ds_write2_b64 v0, v[2:3], v[4:5] offset0:108 offset1:110
	s_waitcnt lgkmcnt(0)
	s_barrier
	s_and_saveexec_b64 s[12:13], vcc
	s_cbranch_execz .LBB0_54
	v_lshl_or_b32 v42, s28, 7, v157
	v_ashrrev_i32_e32 v43, 31, v42
	s_waitcnt vmcnt(0)
	v_mov_b32_e32 v2, v130
	v_mov_b32_e32 v3, v131
	v_mov_b32_e32 v4, v132
	v_mov_b32_e32 v5, v133
	v_mov_b32_e32 v6, v134
	v_mov_b32_e32 v7, v135
	v_mov_b32_e32 v8, v136
	v_mov_b32_e32 v9, v137
	v_mov_b32_e32 v10, v138
	v_mov_b32_e32 v11, v139
	v_mov_b32_e32 v12, v140
	v_mov_b32_e32 v13, v141
	v_mov_b32_e32 v14, v142
	v_mov_b32_e32 v15, v143
	v_mov_b32_e32 v16, v144
	v_mov_b32_e32 v17, v145
	v_mov_b32_e32 v18, v146
	v_mov_b32_e32 v19, v147
	v_mov_b32_e32 v20, v148
	v_mov_b32_e32 v21, v149
	v_mov_b32_e32 v22, v150
	v_mov_b32_e32 v23, v151
	v_mov_b32_e32 v24, v152
	v_mov_b32_e32 v25, v153
	v_mov_b32_e32 v26, v176
	v_mov_b32_e32 v27, v177
	v_mov_b32_e32 v28, v178
	v_mov_b32_e32 v29, v179
	v_mov_b32_e32 v30, v180
	v_mov_b32_e32 v31, v181
	v_mov_b32_e32 v32, v182
	v_mov_b32_e32 v33, v183
	v_mov_b32_e32 v0, v169
	ds_read2_b64 v[36:39], v174 offset0:65 offset1:97
	ds_read2_b64 v[46:49], v174 offset1:32
	s_waitcnt lgkmcnt(1)
	v_and_b32_e32 v35, 0xffff0000, v37
	v_lshlrev_b32_e32 v34, 16, v37
	v_and_b32_e32 v41, 0xffff0000, v36
	v_lshlrev_b32_e32 v40, 16, v36
	v_lshlrev_b32_e32 v36, 16, v39
	v_and_b32_e32 v37, 0xffff0000, v39
	s_waitcnt lgkmcnt(0)
	v_lshlrev_b32_e32 v50, 16, v49
	v_and_b32_e32 v51, 0xffff0000, v49
	v_lshlrev_b32_e32 v52, 16, v47
	v_and_b32_e32 v53, 0xffff0000, v47
	v_lshlrev_b32_e32 v44, 16, v38
	v_and_b32_e32 v45, 0xffff0000, v38
	v_lshlrev_b32_e32 v54, 16, v48
	v_and_b32_e32 v55, 0xffff0000, v48
	v_lshlrev_b32_e32 v56, 16, v46
	v_and_b32_e32 v57, 0xffff0000, v46
	v_lshlrev_b64 v[46:47], 1, v[42:43]
	s_and_saveexec_b64 s[14:15], s[6:7]
	s_cbranch_execz .LBB0_68
	s_add_i32 s10, s27, -2
	v_mad_i64_i32 v[38:39], s[10:11], s10, v216, v[46:47]
	v_lshl_add_u64 v[38:39], v[154:155], 0, v[38:39]
	s_mov_b64 s[16:17], 0
	v_mov_b32_e32 v0, v171
	v_mov_b32_e32 v62, v172
	v_mov_b32_e32 v64, v168
	s_mov_b64 s[22:23], 0x1600
	s_waitcnt vmcnt(0)
	s_branch .LBB0_65

; template <int EPI>
; DI void phase_gemm(const Params& p, const GemmArgs& ga, char* lds) {
;     ...
;       __syncthreads();
;       constexpr int RS = 520;
;       {
;         char* wbase = lds + (wm * 128 + r) * RS + (wn * 64 + 4 * h) * 2;
; #pragma unroll
;         for (int mi = 0; mi < 4; ++mi)
; #pragma unroll
;           for (int ni = 0; ni < 2; ++ni)
; #pragma unroll
;             for (int j = 0; j < 4; ++j) {
;               u32x2 v = {pk_bf16(acc[mi][ni][4 * j], acc[mi][ni][4 * j + 1]), pk_bf16(acc[mi][ni][4 * j + 2], acc[mi][ni][4 * j + 3])};
;               *(u32x2*)(wbase + mi * 32 * RS + (ni * 32 + 8 * j) * 2) = v;
;             }
;       }
;       __syncthreads();
;       {
;         const int q4 = tid & 31, seg = tid >> 5;
;         const int ch = nt * 128 + 4 * q4;
;         const float* cw = p.ffn_conv_w + (size_t)ga.layer * 3 * 5632;
;         const float* cb = p.ffn_conv_b + (size_t)ga.layer * 5632;
;         float4 wg[3], wv[3];
; #pragma unroll
;         for (int t3 = 0; t3 < 3; ++t3) { wg[t3] = *(const float4*)(cw + t3 * 5632 + ch); wv[t3] = *(const float4*)(cw + t3 * 5632 + DFF + ch); }
;         const float4 bg = *(const float4*)(cb + ch);
;         const float4 bv = *(const float4*)(cb + DFF + ch);
.Lg8_u1_join:
.LBB0_172:
	s_and_saveexec_b64 s[14:15], vcc
	v_lshl_or_b32 v158, s28, 7, v157
	v_ashrrev_i32_e32 v159, 31, v158
	v_lshlrev_b64 v[160:161], 2, v[158:159]
	v_readlane_b32 s10, v253, 49
	v_readlane_b32 s11, v253, 50
	s_nop 1
	v_lshl_add_u64 v[130:131], s[10:11], 0, v[160:161]
	v_readlane_b32 s10, v253, 51
	v_readlane_b32 s11, v253, 52
	s_nop 1
	v_lshl_add_u64 v[134:135], s[10:11], 0, v[160:161]
	v_readlane_b32 s10, v254, 11
	v_readlane_b32 s11, v254, 12
	s_nop 1
	v_lshl_add_u64 v[138:139], s[10:11], 0, v[160:161]
	v_readlane_b32 s10, v254, 13
	v_readlane_b32 s11, v254, 14
	s_nop 1
	v_lshl_add_u64 v[142:143], s[10:11], 0, v[160:161]
	v_readlane_b32 s10, v253, 53
	v_readlane_b32 s11, v253, 54
	s_nop 1
	v_lshl_add_u64 v[146:147], s[10:11], 0, v[160:161]
	v_readlane_b32 s10, v253, 55
	v_readlane_b32 s11, v253, 56
	s_nop 1
	v_lshl_add_u64 v[150:151], s[10:11], 0, v[160:161]
	v_readlane_b32 s10, v253, 57
	v_readlane_b32 s11, v253, 58
	s_nop 1
	v_lshl_add_u64 v[176:177], s[10:11], 0, v[160:161]
	v_readlane_b32 s10, v253, 59
	v_readlane_b32 s11, v253, 60
	s_nop 1
	v_lshl_add_u64 v[180:181], s[10:11], 0, v[160:161]
	global_load_dwordx4 v[130:133], v[130:131], off
	global_load_dwordx4 v[134:137], v[134:135], off
	global_load_dwordx4 v[138:141], v[138:139], off
	global_load_dwordx4 v[142:145], v[142:143], off
	global_load_dwordx4 v[146:149], v[146:147], off
	global_load_dwordx4 v[150:153], v[150:151], off
	global_load_dwordx4 v[176:179], v[176:177], off
	global_load_dwordx4 v[180:183], v[180:181], off
	s_or_b64 exec, exec, s[14:15]
	v_add_u32_e32 v0, 0x4000, v173
	s_barrier
	s_nop 8
	v_cvt_pk_bf16_f32 v82, v82, v83
	v_cvt_pk_bf16_f32 v83, v84, v85
	v_cvt_pk_bf16_f32 v84, v86, v87
	v_cvt_pk_bf16_f32 v85, v88, v89
	ds_write2_b64 v0, v[82:83], v[84:85] offset0:32 offset1:34
	v_cvt_pk_bf16_f32 v82, v90, v91
	v_cvt_pk_bf16_f32 v83, v92, v93
	v_cvt_pk_bf16_f32 v66, v66, v67
	v_cvt_pk_bf16_f32 v67, v68, v69
	v_cvt_pk_bf16_f32 v68, v70, v71
	v_cvt_pk_bf16_f32 v69, v72, v73
	v_cvt_pk_bf16_f32 v84, v94, v95
	v_cvt_pk_bf16_f32 v85, v96, v97
	ds_write2_b64 v0, v[66:67], v[68:69] offset0:40 offset1:42
	v_cvt_pk_bf16_f32 v66, v74, v75
	v_cvt_pk_bf16_f32 v67, v76, v77
	v_cvt_pk_bf16_f32 v68, v78, v79
	v_cvt_pk_bf16_f32 v69, v80, v81
	ds_write2_b64 v0, v[82:83], v[84:85] offset0:36 offset1:38
	ds_write2_b64 v0, v[66:67], v[68:69] offset0:44 offset1:46
	v_cvt_pk_bf16_f32 v50, v50, v51
	v_cvt_pk_bf16_f32 v51, v52, v53
	v_cvt_pk_bf16_f32 v52, v54, v55
	v_cvt_pk_bf16_f32 v53, v56, v57
	v_add_u32_e32 v0, 0x8000, v173
	v_cvt_pk_bf16_f32 v34, v34, v35
	v_cvt_pk_bf16_f32 v35, v36, v37
	v_cvt_pk_bf16_f32 v36, v38, v39
	v_cvt_pk_bf16_f32 v37, v40, v41
	ds_write2_b64 v0, v[50:51], v[52:53] offset0:64 offset1:66
	v_cvt_pk_bf16_f32 v50, v58, v59
	v_cvt_pk_bf16_f32 v51, v60, v61
	v_cvt_pk_bf16_f32 v52, v62, v63
	v_cvt_pk_bf16_f32 v53, v64, v65
	ds_write2_b64 v0, v[34:35], v[36:37] offset0:72 offset1:74
	v_cvt_pk_bf16_f32 v34, v42, v43
	v_cvt_pk_bf16_f32 v35, v44, v45
	v_cvt_pk_bf16_f32 v36, v46, v47
	v_cvt_pk_bf16_f32 v37, v48, v49
	v_cvt_pk_bf16_f32 v114, v114, v115
	v_cvt_pk_bf16_f32 v115, v116, v117
	v_cvt_pk_bf16_f32 v116, v118, v119
	v_cvt_pk_bf16_f32 v117, v120, v121
	v_cvt_pk_bf16_f32 v98, v98, v99
	v_cvt_pk_bf16_f32 v99, v100, v101
	v_cvt_pk_bf16_f32 v100, v102, v103
	v_cvt_pk_bf16_f32 v101, v104, v105
	ds_write2_b64 v0, v[50:51], v[52:53] offset0:68 offset1:70
	ds_write2_b64 v0, v[34:35], v[36:37] offset0:76 offset1:78
	v_cvt_pk_bf16_f32 v18, v18, v19
	v_cvt_pk_bf16_f32 v19, v20, v21
	v_cvt_pk_bf16_f32 v20, v22, v23
	v_cvt_pk_bf16_f32 v21, v24, v25
	v_add_u32_e32 v0, 0xc000, v173
	v_cvt_pk_bf16_f32 v2, v2, v3
	v_cvt_pk_bf16_f32 v3, v4, v5
	v_cvt_pk_bf16_f32 v4, v6, v7
	v_cvt_pk_bf16_f32 v5, v8, v9
	ds_write2_b64 v173, v[114:115], v[116:117] offset1:2
	v_cvt_pk_bf16_f32 v114, v122, v123
	v_cvt_pk_bf16_f32 v115, v124, v125
	v_cvt_pk_bf16_f32 v116, v126, v127
	v_cvt_pk_bf16_f32 v117, v128, v129
	ds_write2_b64 v173, v[98:99], v[100:101] offset0:8 offset1:10
	v_cvt_pk_bf16_f32 v98, v106, v107
	v_cvt_pk_bf16_f32 v99, v108, v109
	v_cvt_pk_bf16_f32 v100, v110, v111
	v_cvt_pk_bf16_f32 v101, v112, v113
	ds_write2_b64 v0, v[18:19], v[20:21] offset0:96 offset1:98
	v_cvt_pk_bf16_f32 v18, v26, v27
	v_cvt_pk_bf16_f32 v19, v28, v29
	v_cvt_pk_bf16_f32 v20, v30, v31
	v_cvt_pk_bf16_f32 v21, v32, v33
	ds_write2_b64 v0, v[2:3], v[4:5] offset0:104 offset1:106
	v_cvt_pk_bf16_f32 v2, v10, v11
	v_cvt_pk_bf16_f32 v3, v12, v13
	v_cvt_pk_bf16_f32 v4, v14, v15
	v_cvt_pk_bf16_f32 v5, v16, v17
	ds_write2_b64 v173, v[114:115], v[116:117] offset0:4 offset1:6
	ds_write2_b64 v173, v[98:99], v[100:101] offset0:12 offset1:14
	ds_write2_b64 v0, v[18:19], v[20:21] offset0:100 offset1:102
	ds_write2_b64 v0, v[2:3], v[4:5] offset0:108 offset1:110
	s_waitcnt lgkmcnt(0)
	s_barrier
; template <int EPI>
; DI void phase_gemm(const Params& p, const GemmArgs& ga, char* lds) {
;     ...
;         float4 wg[3], wv[3];
; #pragma unroll
;         for (int t3 = 0; t3 < 3; ++t3) { wg[t3] = *(const float4*)(cw + t3 * 5632 + ch); wv[t3] = *(const float4*)(cw + t3 * 5632 + DFF + ch); }
;         const float4 bg = *(const float4*)(cb + ch);
;         const float4 bv = *(const float4*)(cb + DFF + ch);
;         const char* gbase = lds + q4 * 8;
;         const char* vbase = lds + 256 + q4 * 8;
;         const int R0 = 1 + seg * 16;
;         const int Rend = (R0 + 16 < 255) ? (R0 + 16) : 255;
;         auto ld4 = [&](const char* b_, int R) -> float4 {
;           const u32x2 u = *(const u32x2*)(b_ + R * RS);
;           float4 f = {__uint_as_float(u.x << 16), __uint_as_float(u.x & 0xffff0000u), __uint_as_float(u.y << 16), __uint_as_float(u.y & 0xffff0000u)};
;           return f;
;         };
;         float4 pg = ld4(gbase, R0 - 1), pvv = ld4(vbase, R0 - 1);
;         float4 cg_ = ld4(gbase, R0), cv_ = ld4(vbase, R0);
	s_and_saveexec_b64 s[12:13], vcc
	s_mov_b64 s[36:37], 0x27c0080
	s_cbranch_execz .LBB0_165
	v_lshl_or_b32 v42, s28, 7, v157
	v_ashrrev_i32_e32 v43, 31, v42
	s_waitcnt vmcnt(0)
	v_mov_b32_e32 v6, v130
	v_mov_b32_e32 v7, v131
	v_mov_b32_e32 v8, v132
	v_mov_b32_e32 v9, v133
	v_mov_b32_e32 v10, v134
	v_mov_b32_e32 v11, v135
	v_mov_b32_e32 v12, v136
	v_mov_b32_e32 v13, v137
	v_mov_b32_e32 v2, v138
	v_mov_b32_e32 v3, v139
	v_mov_b32_e32 v4, v140
	v_mov_b32_e32 v5, v141
	v_mov_b32_e32 v26, v142
	v_mov_b32_e32 v27, v143
	v_mov_b32_e32 v28, v144
	v_mov_b32_e32 v29, v145
	v_mov_b32_e32 v14, v146
	v_mov_b32_e32 v15, v147
	v_mov_b32_e32 v16, v148
	v_mov_b32_e32 v17, v149
	v_mov_b32_e32 v18, v150
	v_mov_b32_e32 v19, v151
	v_mov_b32_e32 v20, v152
	v_mov_b32_e32 v21, v153
	v_mov_b32_e32 v22, v176
	v_mov_b32_e32 v23, v177
	v_mov_b32_e32 v24, v178
	v_mov_b32_e32 v25, v179
	v_mov_b32_e32 v30, v180
	v_mov_b32_e32 v31, v181
	v_mov_b32_e32 v32, v182
	v_mov_b32_e32 v33, v183
	v_readlane_b32 s36, v254, 11
	v_readlane_b32 s37, v254, 12
	v_readlane_b32 s38, v254, 13
	v_readlane_b32 s39, v254, 14
	v_lshlrev_b64 v[46:47], 1, v[42:43]
	v_mov_b32_e32 v0, v169
	v_readlane_b32 s40, v254, 15
	v_readlane_b32 s41, v254, 16
	v_readlane_b32 s42, v254, 17
	v_readlane_b32 s43, v254, 18
	ds_read2_b64 v[36:39], v174 offset0:65 offset1:97
	ds_read2_b64 v[58:61], v174 offset1:32
	s_waitcnt lgkmcnt(1)
	v_and_b32_e32 v35, 0xffff0000, v37
	v_lshlrev_b32_e32 v34, 16, v37
	v_and_b32_e32 v41, 0xffff0000, v36
	v_lshlrev_b32_e32 v40, 16, v36
	v_lshlrev_b32_e32 v36, 16, v39
	v_and_b32_e32 v37, 0xffff0000, v39
	s_waitcnt lgkmcnt(0)
	v_lshlrev_b32_e32 v48, 16, v61
	v_and_b32_e32 v49, 0xffff0000, v61
	v_lshlrev_b32_e32 v52, 16, v59
	v_and_b32_e32 v53, 0xffff0000, v59
	v_lshlrev_b32_e32 v44, 16, v38
	v_and_b32_e32 v45, 0xffff0000, v38
	v_lshlrev_b32_e32 v54, 16, v60
	v_and_b32_e32 v55, 0xffff0000, v60
	v_lshlrev_b32_e32 v56, 16, v58
	v_and_b32_e32 v57, 0xffff0000, v58
	s_and_saveexec_b64 s[14:15], s[6:7]
	s_cbranch_execz .LBB0_179
	s_add_i32 s10, s27, -2
	v_mad_i64_i32 v[38:39], s[10:11], s10, v216, v[46:47]
	v_lshl_add_u64 v[38:39], v[154:155], 0, v[38:39]
	s_mov_b64 s[16:17], 0
	v_mov_b32_e32 v0, v171
	v_mov_b32_e32 v62, v172
	v_mov_b32_e32 v64, v168
	s_mov_b64 s[22:23], 0x1600
	s_waitcnt vmcnt(0)
	s_branch .LBB0_176
